# v54 + attention V-tile staging assignment remapped (thread bit 2 and bit 4 swapped) so each 8-lane ds_write_b128 group covers 128 contiguous bytes: conflict-free V writes, LDS layout unchanged
# speedup vs baseline: 1.0024x; 1.0024x over previous
; __device__ __forceinline__ int tid_opaque() { int t = (int)threadIdx.x; asm volatile("" : "+v"(t)); return t; }
; __device__ __forceinline__ int v_st(int k, int c) { const int kk = (k & ~0xC) | ((k & 4) << 1) | ((k & 8) >> 1); return ((kk >> 3) * 4 + (c >> 5)) * 512 + ((kk & 7) * 32 + (c & 31)) * 2; }
; __device__ __forceinline__ int v_rd_base(int lane) { return ((lane & 3) << 3) | (((lane >> 2) & 3) << 6) | (((lane >> 4) & 1) << 5) | (((lane >> 5) & 1) << 8); }
; #define SLOAD(i, k0) do { sv0[i] = *reinterpret_cast<const bf16x8*>(&Vh[(size_t)((k0) + sr) * LDQ + sc]); sv1[i] = *reinterpret_cast<const bf16x8*>(&Vh[(size_t)((k0) + 32 + sr) * LDQ + sc]); \
;     sk0[i] = *reinterpret_cast<const bf16x8*>(&Kh[(size_t)((k0) + kr) * LDQ + kc]); } while (0)
; #define SWAIT() asm volatile("s_waitcnt vmcnt(3)" ::: "memory")
; __device__ __forceinline__ void attn_unit(const bf16_t* __restrict__ Qb, const bf16_t* __restrict__ Kh, const bf16_t* __restrict__ Vh, bf16_t* __restrict__ Ob, int qpos0, float slope2, char* lds, const int NT) {
;     const int tid = tid_opaque(), wid = tid >> 6, lane = tid & 63, r32 = lane & 31, hi = lane >> 5;
;     char* V_lds = lds; char* K_lds = lds + 2 * SHM_V;
;     float* wsf = (float*)(lds + 2 * SHM_V + 2 * SHM_K) + wid * 64; float* li_l = wsf; float* al_l = wsf + 32;
;     float m_reg = -1e30f, l_reg = 0; f32x16 o[4] = {}; bf16x8 qr[4];
;     const bf16_t* Qw = Qb + (size_t)(wid * QBLK + r32) * LDQ + hi * 8;
; #pragma unroll
;     for (int d0 = 0; d0 < 4; ++d0) qr[d0] = *reinterpret_cast<const bf16x8*>(Qw + d0 * 16);
;     const float qposf = (float)(qpos0 + wid * QBLK + r32);
;     const int sr = tid >> 4, sc = (tid & 15) * 8, vst0 = v_st(sr, sc), vst1 = v_st(32 + sr, sc);
;     const int kr = tid >> 3, kc = (tid & 7) * 8, kst = KSWZ(kr, kc * 2);
;     const int vb0 = (int)(uintptr_t)V_lds + v_rd_base(lane);
;     bf16x8 sv0[2], sv1[2], sk0[2];
;     ...
;     f32x16 pA0, pA1, pB0, pB1; float mnA, mnB, alA, alB; bf16x8 pa0, pa1, pa2, pa3;
;     __syncthreads();
;     SLOAD(0, 0); asm volatile("s_waitcnt vmcnt(0)" ::: "memory"); SWRITE(0, 0); __syncthreads();
;     qkt(pA0, pA1, K_lds, qr, r32, hi); partialSM(pA0, pA1, m_reg, mnA, alA, qposf, slope2, hi);
;     SLOAD(1, KVBLK); if (2 < NT) SLOAD(0, 2 * KVBLK);
;     SWAIT(); SWRITE(1, 1); __syncthreads();
.LBB0_152:
	s_or_b64 exec, exec, s[0:1]
	v_lshlrev_b32_e32 v2, 7, v203
	v_ashrrev_i32_e32 v81, 31, v80
	v_and_b32_e32 v112, 0x2000, v2
	v_lshlrev_b64 v[2:3], 6, v[80:81]
	s_movk_i32 s0, 0x180
	v_lshl_add_u64 v[2:3], v[2:3], 0, v[112:113]
	v_mov_b64_e32 v[4:5], s[64:65]
	s_movk_i32 s2, 0xc00
	v_or_b32_e32 v205, v112, v0
	v_bitop3_b32 v8, v203, s0, v203 bitop3:0xc
	v_mad_u64_u32 v[6:7], s[0:1], v2, s2, v[4:5]
	v_bfe_u32 v169, v203, 5, 1
	v_mad_i32_i24 v7, v3, s2, v7
	v_mad_u64_u32 v[2:3], s[0:1], v205, s2, v[4:5]
	v_lshlrev_b32_e32 v166, 1, v8
	v_mov_b32_e32 v167, v113
	v_lshlrev_b32_e32 v4, 6, v80
	v_mov_b32_e32 v81, v154
	v_lshl_add_u64 v[2:3], v[2:3], 0, v[166:167]
	v_lshlrev_b32_e32 v112, 7, v169
	v_sub_u32_e32 v4, v0, v4
	s_movk_i32 s0, 0xffe0
	v_ashrrev_i32_e32 v0, 1, v81
	v_lshl_add_u64 v[2:3], v[2:3], 0, v[112:113]
	v_bfe_u32 v206, v81, 5, 1
	v_and_b32_e32 v168, 0xffffffe0, v0
	v_bfi_b32 v0, s0, v0, v81
	v_sub_u32_e32 v207, v1, v80
	v_mad_i64_i32 v[0:1], s[0:1], v0, s2, v[2:3]
	v_lshlrev_b32_e32 v38, 4, v206
	v_mov_b32_e32 v39, v113
	v_and_b32_e32 v204, 31, v81
	v_lshl_add_u64 v[0:1], v[0:1], 0, v[38:39]
	global_load_dwordx4 v[126:129], v[0:1], off
	global_load_dwordx4 v[122:125], v[0:1], off offset:32
	global_load_dwordx4 v[118:121], v[0:1], off offset:64
	global_load_dwordx4 v[114:117], v[0:1], off offset:96
	v_or_b32_e32 v0, v204, v4
	v_lshrrev_b32_e32 v219, 2, v81
	v_lshrrev_b32_e32 v220, 4, v81
	v_xor_b32_e32 v219, v219, v220
	v_and_b32_e32 v219, 1, v219
	v_mul_u32_u24_e32 v219, 20, v219
	v_xor_b32_e32 v220, v81, v219
	v_ashrrev_i32_e32 v82, 4, v220
	v_add_u32_e32 v0, v0, v168
	v_and_b32_e32 v1, 0xfffff0, v82
	v_lshlrev_b32_e32 v3, 1, v82
	v_cvt_f32_i32_e32 v208, v0
	v_lshlrev_b32_e32 v0, 3, v81
	v_and_or_b32 v1, v3, 8, v1
	v_lshrrev_b32_e32 v3, 1, v82
	v_lshrrev_b32_e32 v1, 1, v1
	v_bfe_u32 v4, v220, 2, 2
	v_and_b32_e32 v5, 3, v82
	v_or_b32_e32 v1, v1, v4
	v_and_or_b32 v3, v3, 4, v5
	v_lshlrev_b32_e32 v5, 4, v81
	v_lshl_add_u64 v[34:35], v[6:7], 0, v[166:167]
	v_lshlrev_b32_e32 v1, 9, v1
	v_lshlrev_b32_e32 v3, 6, v3
	v_and_b32_e32 v6, 48, v5
	v_add_u32_e32 v8, 32, v82
	v_or3_b32 v7, v1, v3, v6
	v_and_b32_e32 v1, 0xfffff0, v8
	v_lshlrev_b32_e32 v9, 1, v8
	v_and_or_b32 v1, v9, 8, v1
	v_lshrrev_b32_e32 v1, 1, v1
	v_lshlrev_b32_e32 v2, 3, v220
	v_and_b32_e32 v2, 0x78, v2
	v_or_b32_e32 v1, v1, v4
	v_ashrrev_i32_e32 v83, 3, v81
	v_and_b32_e32 v0, 56, v0
	v_lshlrev_b32_e32 v1, 9, v1
	v_lshlrev_b32_e32 v36, 1, v0
	v_lshlrev_b32_e32 v0, 4, v83
	v_or3_b32 v3, v1, v3, v6
	v_lshlrev_b32_e32 v1, 7, v83
	v_and_b32_e32 v0, 0x70, v0
	v_and_b32_e32 v219, 16, v83
	v_xor_b32_e32 v0, v0, v219
	v_lshl_add_u64 v[32:33], v[34:35], 0, v[112:113]
	v_bitop3_b32 v4, v36, v1, v0 bitop3:0xde
	v_mad_i64_i32 v[0:1], s[0:1], v82, s2, v[34:35]
	v_lshlrev_b32_e32 v112, 1, v2
	v_lshl_add_u64 v[0:1], v[0:1], 0, v[112:113]
	s_barrier
	global_load_dwordx4 v[130:133], v[0:1], off offset:2048
	v_mad_i64_i32 v[0:1], s[0:1], v8, s2, v[34:35]
	v_lshl_add_u64 v[0:1], v[0:1], 0, v[112:113]
	global_load_dwordx4 v[134:137], v[0:1], off offset:2048
	v_mad_i64_i32 v[0:1], s[0:1], v83, s2, v[32:33]
	v_mov_b32_e32 v37, v113
	v_lshl_add_u64 v[0:1], v[0:1], 0, v[36:37]
	global_load_dwordx4 v[138:141], v[0:1], off offset:1024
	v_lshlrev_b32_e32 v39, 7, v204
	v_and_b32_e32 v48, 0x70, v5
	v_and_b32_e32 v219, 16, v204
	v_xor_b32_e32 v48, v48, v219
	v_bitop3_b32 v0, v38, v39, v48 bitop3:0xde
	v_add_u32_e32 v219, 0, v7
	v_add_u32_e32 v220, 0, v3
	v_add_u32_e32 v221, 0, v4
	v_add_u32_e32 v215, 0, v0
	s_waitcnt vmcnt(0)
	v_or_b32_e32 v40, 32, v38
	v_bitop3_b32 v40, v40, v39, v48 bitop3:0xde
	v_add_u32_e32 v214, 0, v40
	v_cmp_lt_i32_e64 s[6:7], 2, v207
	s_waitcnt vmcnt(2)
	ds_write_b128 v219, v[130:133]
	s_waitcnt vmcnt(1)
	ds_write_b128 v220, v[134:137]
	s_waitcnt vmcnt(0)
	ds_write_b128 v221, v[138:141] offset:32768
	s_waitcnt lgkmcnt(0)
	s_barrier
	ds_read_b128 v[0:3], v215 offset:32768
	ds_read_b128 v[4:7], v215 offset:36864
	s_waitcnt lgkmcnt(1)
	v_mfma_f32_32x32x16_bf16 v[16:31], v[0:3], v[126:129], 0
	ds_read_b128 v[40:43], v214 offset:32768
	ds_read_b128 v[44:47], v214 offset:36864
	s_waitcnt lgkmcnt(2)
	v_mfma_f32_32x32x16_bf16 v[0:15], v[4:7], v[126:129], 0
	s_waitcnt lgkmcnt(1)
	v_mfma_f32_32x32x16_bf16 v[16:31], v[40:43], v[122:125], v[16:31]
	v_or_b32_e32 v40, 64, v38
	v_bitop3_b32 v40, v40, v39, v48 bitop3:0xde
	v_add_u32_e32 v216, 0, v40
	v_or_b32_e32 v38, 0x60, v38
	v_bitop3_b32 v38, v38, v39, v48 bitop3:0xde
	v_add_u32_e32 v217, 0, v38
	s_waitcnt lgkmcnt(0)
	v_mfma_f32_32x32x16_bf16 v[0:15], v[44:47], v[122:125], v[0:15]
	ds_read_b128 v[40:43], v216 offset:32768
	ds_read_b128 v[44:47], v216 offset:36864
	s_waitcnt lgkmcnt(1)
	v_mfma_f32_32x32x16_bf16 v[16:31], v[40:43], v[118:121], v[16:31]
	s_waitcnt lgkmcnt(0)
	v_mfma_f32_32x32x16_bf16 v[0:15], v[44:47], v[118:121], v[0:15]
	ds_read_b128 v[38:41], v217 offset:32768
	ds_read_b128 v[42:45], v217 offset:36864
	s_waitcnt lgkmcnt(1)
	v_mfma_f32_32x32x16_bf16 v[16:31], v[38:41], v[114:117], v[16:31]
	v_lshlrev_b32_e32 v38, 2, v206
	v_cvt_f32_ubyte0_e32 v209, v38
	v_sub_f32_e32 v52, v208, v209
	v_add_f32_e32 v53, -1.0, v52
	s_waitcnt lgkmcnt(0)
; #define SLOAD(i, k0) do { sv0[i] = *reinterpret_cast<const bf16x8*>(&Vh[(size_t)((k0) + sr) * LDQ + sc]); sv1[i] = *reinterpret_cast<const bf16x8*>(&Vh[(size_t)((k0) + 32 + sr) * LDQ + sc]); \
;     sk0[i] = *reinterpret_cast<const bf16x8*>(&Kh[(size_t)((k0) + kr) * LDQ + kc]); } while (0)
; __device__ __forceinline__ void partialSM(f32x16& p0, f32x16& p1, float& m_reg, float& mn, float& alpha, float dq, float slope2, int hi) {
;     const float d0 = dq - (float)(4 * hi);
; #pragma unroll
;     for (int r = 0; r < 16; ++r) { const float c = (float)((r & 3) + 8 * (r >> 2)); p0[r] = fmaf(-slope2, fabsf(d0 - c), p0[r]); p1[r] = fmaf(-slope2, fabsf(d0 - c - 32.0f), p1[r]); }
;     float pmax = p0[0];
; #pragma unroll
;     for (int r = 1; r < 16; ++r) pmax = fmaxf(pmax, p0[r]);
; #pragma unroll
;     for (int r = 0; r < 16; ++r) pmax = fmaxf(pmax, p1[r]);
;     { auto rr = __builtin_amdgcn_permlane32_swap(__float_as_uint(pmax), __float_as_uint(pmax), false, false); pmax = fmaxf(__uint_as_float(rr[0]), __uint_as_float(rr[1])); }
;     if (__builtin_expect(__all(pmax - m_reg <= THR), 1)) { mn = m_reg; alpha = 1.f; }
;     else { mn = fmaxf(m_reg, pmax); alpha = __builtin_amdgcn_exp2f(m_reg - mn); m_reg = mn; }
; #pragma unroll
;     for (int r = 0; r < 16; ++r) { p0[r] = p0[r] - mn; p1[r] = p1[r] - mn; }
; #pragma unroll
;     for (int r = 0; r < 16; ++r) p0[r] = __builtin_amdgcn_exp2f(p0[r]);
; }
; __device__ __forceinline__ void attn_unit(const bf16_t* __restrict__ Qb, const bf16_t* __restrict__ Kh, const bf16_t* __restrict__ Vh, bf16_t* __restrict__ Ob, int qpos0, float slope2, char* lds, const int NT) {
;     ...
;     qkt(pA0, pA1, K_lds, qr, r32, hi); partialSM(pA0, pA1, m_reg, mnA, alA, qposf, slope2, hi);
;     SLOAD(1, KVBLK); if (2 < NT) SLOAD(0, 2 * KVBLK);
	v_mfma_f32_32x32x16_bf16 v[0:15], v[42:45], v[114:117], v[0:15]
	s_nop 5
	v_fma_f32 v39, -v170, |v52|, v16
	v_fma_f32 v40, -v170, |v53|, v17
	v_add_f32_e64 v16, v52, s72
	v_add_f32_e64 v17, v53, s72
	v_max_f32_e32 v43, v39, v40
	v_and_b32_e32 v17, 0x7fffffff, v17
	v_and_b32_e32 v16, 0x7fffffff, v16
	v_pk_fma_f32 v[16:17], v[170:171], v[16:17], v[0:1] op_sel_hi:[0,1,1] neg_lo:[1,0,0] neg_hi:[1,0,0]
	v_pk_add_f32 v[0:1], v[52:53], s[38:39] op_sel_hi:[0,1]
	v_fma_f32 v41, -v170, |v0|, v18
	v_fma_f32 v42, -v170, |v1|, v19
	v_pk_add_f32 v[0:1], v[0:1], s[72:73] op_sel_hi:[1,0]
	s_nop 0
	v_and_b32_e32 v1, 0x7fffffff, v1
	v_and_b32_e32 v0, 0x7fffffff, v0
	v_pk_fma_f32 v[18:19], v[170:171], v[0:1], v[2:3] op_sel_hi:[0,1,1] neg_lo:[1,0,0] neg_hi:[1,0,0]
	v_pk_add_f32 v[0:1], v[52:53], s[30:31] op_sel_hi:[0,1]
	v_max3_f32 v2, v43, v41, v42
	v_fma_f32 v43, -v170, |v0|, v20
	v_fma_f32 v44, -v170, |v1|, v21
	v_pk_add_f32 v[0:1], v[0:1], s[72:73] op_sel_hi:[1,0]
	v_max3_f32 v2, v2, v43, v44
	v_and_b32_e32 v1, 0x7fffffff, v1
	v_and_b32_e32 v0, 0x7fffffff, v0
	v_pk_fma_f32 v[20:21], v[170:171], v[0:1], v[4:5] op_sel_hi:[0,1,1] neg_lo:[1,0,0] neg_hi:[1,0,0]
	v_pk_add_f32 v[0:1], v[52:53], s[62:63] op_sel_hi:[0,1]
	v_fma_f32 v45, -v170, |v0|, v22
	v_fma_f32 v46, -v170, |v1|, v23
	v_pk_add_f32 v[0:1], v[0:1], s[72:73] op_sel_hi:[1,0]
	v_max3_f32 v2, v2, v45, v46
	v_and_b32_e32 v1, 0x7fffffff, v1
	v_and_b32_e32 v0, 0x7fffffff, v0
	v_pk_fma_f32 v[22:23], v[170:171], v[0:1], v[6:7] op_sel_hi:[0,1,1] neg_lo:[1,0,0] neg_hi:[1,0,0]
	v_pk_add_f32 v[0:1], v[52:53], s[40:41] op_sel_hi:[0,1]
	v_fma_f32 v47, -v170, |v0|, v24
	v_fma_f32 v48, -v170, |v1|, v25
	v_pk_add_f32 v[0:1], v[0:1], s[72:73] op_sel_hi:[1,0]
	v_max3_f32 v2, v2, v47, v48
	v_and_b32_e32 v1, 0x7fffffff, v1
	v_and_b32_e32 v0, 0x7fffffff, v0
	v_pk_fma_f32 v[24:25], v[170:171], v[0:1], v[8:9] op_sel_hi:[0,1,1] neg_lo:[1,0,0] neg_hi:[1,0,0]
	v_pk_add_f32 v[0:1], v[52:53], s[42:43] op_sel_hi:[0,1]
	v_fma_f32 v49, -v170, |v0|, v26
	v_fma_f32 v50, -v170, |v1|, v27
	v_pk_add_f32 v[0:1], v[0:1], s[72:73] op_sel_hi:[1,0]
	v_max3_f32 v2, v2, v49, v50
	v_and_b32_e32 v1, 0x7fffffff, v1
	v_and_b32_e32 v0, 0x7fffffff, v0
	v_pk_fma_f32 v[26:27], v[170:171], v[0:1], v[10:11] op_sel_hi:[0,1,1] neg_lo:[1,0,0] neg_hi:[1,0,0]
	v_pk_add_f32 v[0:1], v[52:53], s[44:45] op_sel_hi:[0,1]
	v_fma_f32 v28, -v170, |v0|, v28
	v_fma_f32 v29, -v170, |v1|, v29
	v_pk_add_f32 v[0:1], v[0:1], s[72:73] op_sel_hi:[1,0]
	v_max3_f32 v2, v2, v28, v29
	v_and_b32_e32 v1, 0x7fffffff, v1
	v_and_b32_e32 v0, 0x7fffffff, v0
	v_pk_fma_f32 v[12:13], v[170:171], v[0:1], v[12:13] op_sel_hi:[0,1,1] neg_lo:[1,0,0] neg_hi:[1,0,0]
	v_pk_add_f32 v[0:1], v[52:53], s[48:49] op_sel_hi:[0,1]
	v_fma_f32 v30, -v170, |v0|, v30
	v_fma_f32 v31, -v170, |v1|, v31
	v_pk_add_f32 v[0:1], v[0:1], s[72:73] op_sel_hi:[1,0]
	v_add_u32_e32 v4, 0x60, v82
	v_and_b32_e32 v1, 0x7fffffff, v1
	v_and_b32_e32 v0, 0x7fffffff, v0
	v_pk_fma_f32 v[14:15], v[170:171], v[0:1], v[14:15] op_sel_hi:[0,1,1] neg_lo:[1,0,0] neg_hi:[1,0,0]
	v_max3_f32 v0, v2, v30, v31
	v_max3_f32 v0, v0, v16, v17
	v_max3_f32 v0, v0, v18, v19
	v_max3_f32 v0, v0, v20, v21
	v_max3_f32 v0, v0, v22, v23
	v_max3_f32 v0, v0, v24, v25
	v_max3_f32 v0, v0, v26, v27
	v_max3_f32 v0, v0, v12, v13
	v_max3_f32 v0, v0, v14, v15
	v_mov_b32_e32 v1, v0
	s_nop 1
	v_permlane32_swap_b32_e32 v0, v1
	v_max_f32_e32 v1, v1, v1
	v_max_f32_e32 v0, v0, v0
	v_max_f32_e32 v51, v0, v1
	v_add_f32_e32 v0, 0x7149f2ca, v51
	v_cmp_ge_f32_e32 vcc, s68, v0
	v_add_u32_e32 v0, 64, v82
	v_add_u32_e32 v8, 64, v83
	v_mad_i64_i32 v[0:1], s[0:1], v0, s2, v[34:35]
	v_mad_i64_i32 v[4:5], s[0:1], v4, s2, v[34:35]
	v_mad_i64_i32 v[8:9], s[0:1], v8, s2, v[32:33]
	v_lshl_add_u64 v[0:1], v[0:1], 0, v[112:113]
	v_lshl_add_u64 v[4:5], v[4:5], 0, v[112:113]
	v_lshl_add_u64 v[8:9], v[8:9], 0, v[36:37]
	global_load_dwordx4 v[0:3], v[0:1], off offset:2048
	s_cmp_eq_u64 vcc, exec
	global_load_dwordx4 v[4:7], v[4:5], off offset:2048
	s_cselect_b64 vcc, -1, 0
	global_load_dwordx4 v[8:11], v[8:9], off offset:1024
	s_and_saveexec_b64 s[0:1], s[6:7]
	s_cbranch_execz .LBB0_154
	v_add_u32_e32 v52, 0x80, v82
	s_movk_i32 s8, 0xc00
	v_add_u32_e32 v54, 0xa0, v82
	v_mad_i64_i32 v[52:53], s[2:3], v52, s8, v[34:35]
	v_mad_i64_i32 v[34:35], s[2:3], v54, s8, v[34:35]
	v_lshl_add_u64 v[52:53], v[52:53], 0, v[112:113]
	v_lshl_add_u64 v[34:35], v[34:35], 0, v[112:113]
	global_load_dwordx4 v[130:133], v[52:53], off offset:2048
	global_load_dwordx4 v[134:137], v[34:35], off offset:2048
	v_add_u32_e32 v34, 0x80, v83
	v_mad_i64_i32 v[32:33], s[2:3], v34, s8, v[32:33]
	v_lshl_add_u64 v[32:33], v[32:33], 0, v[36:37]
	global_load_dwordx4 v[138:141], v[32:33], off offset:1024
; __device__ __forceinline__ int v_st(int k, int c) { const int kk = (k & ~0xC) | ((k & 4) << 1) | ((k & 8) >> 1); return ((kk >> 3) * 4 + (c >> 5)) * 512 + ((kk & 7) * 32 + (c & 31)) * 2; }
; __device__ __forceinline__ int v_rd_base(int lane) { return ((lane & 3) << 3) | (((lane >> 2) & 3) << 6) | (((lane >> 4) & 1) << 5) | (((lane >> 5) & 1) << 8); }
; #define SLOAD(i, k0) do { sv0[i] = *reinterpret_cast<const bf16x8*>(&Vh[(size_t)((k0) + sr) * LDQ + sc]); sv1[i] = *reinterpret_cast<const bf16x8*>(&Vh[(size_t)((k0) + 32 + sr) * LDQ + sc]); \
;     sk0[i] = *reinterpret_cast<const bf16x8*>(&Kh[(size_t)((k0) + kr) * LDQ + kc]); } while (0)
; #define SWRITE(b, i) do { *(bf16x8*)(V_lds + (b) * SHM_V + vst0) = sv0[i]; *(bf16x8*)(V_lds + (b) * SHM_V + vst1) = sv1[i]; *(bf16x8*)(K_lds + (b) * SHM_K + kst) = sk0[i]; } while (0)
; #define SWAIT() asm volatile("s_waitcnt vmcnt(3)" ::: "memory")
; __device__ __forceinline__ void attn_unit(const bf16_t* __restrict__ Qb, const bf16_t* __restrict__ Kh, const bf16_t* __restrict__ Vh, bf16_t* __restrict__ Ob, int qpos0, float slope2, char* lds, const int NT) {
;     ...
;     float m_reg = -1e30f, l_reg = 0; f32x16 o[4] = {}; bf16x8 qr[4];
;     const bf16_t* Qw = Qb + (size_t)(wid * QBLK + r32) * LDQ + hi * 8;
; #pragma unroll
;     for (int d0 = 0; d0 < 4; ++d0) qr[d0] = *reinterpret_cast<const bf16x8*>(Qw + d0 * 16);
;     const float qposf = (float)(qpos0 + wid * QBLK + r32);
;     const int sr = tid >> 4, sc = (tid & 15) * 8, vst0 = v_st(sr, sc), vst1 = v_st(32 + sr, sc);
;     const int kr = tid >> 3, kc = (tid & 7) * 8, kst = KSWZ(kr, kc * 2);
;     const int vb0 = (int)(uintptr_t)V_lds + v_rd_base(lane);
;     bf16x8 sv0[2], sv1[2], sk0[2];
;     ...
;     f32x16 pA0, pA1, pB0, pB1; float mnA, mnB, alA, alB; bf16x8 pa0, pa1, pa2, pa3;
;     __syncthreads();
;     SLOAD(0, 0); asm volatile("s_waitcnt vmcnt(0)" ::: "memory"); SWRITE(0, 0); __syncthreads();
;     qkt(pA0, pA1, K_lds, qr, r32, hi); partialSM(pA0, pA1, m_reg, mnA, alA, qposf, slope2, hi);
;     SLOAD(1, KVBLK); if (2 < NT) SLOAD(0, 2 * KVBLK);
;     SWAIT(); SWRITE(1, 1); __syncthreads();
.LBB0_154:
	s_or_b64 exec, exec, s[0:1]
	v_max_f32_e32 v32, 0xf149f2ca, v51
	v_cndmask_b32_e32 v223, v32, v188, vcc
	v_and_b32_e32 v210, 63, v81
	v_sub_f32_e32 v30, v30, v223
	v_sub_f32_e32 v29, v29, v223
	v_sub_f32_e32 v31, v31, v223
	v_exp_f32_e32 v142, v30
	v_lshlrev_b32_e32 v30, 4, v210
	v_exp_f32_e32 v146, v29
	v_exp_f32_e32 v144, v31
	v_lshlrev_b32_e32 v29, 3, v210
	v_and_b32_e32 v30, 0xc0, v30
	v_lshlrev_b32_e32 v31, 1, v210
	v_and_or_b32 v30, v29, 24, v30
	v_and_b32_e32 v31, 32, v31
	v_and_b32_e32 v29, 0x100, v29
	v_or3_b32 v218, v30, v31, v29
	v_sub_f32_e32 v29, 0xf149f2ca, v32
	v_sub_f32_e32 v33, v39, v223
	v_sub_f32_e32 v34, v40, v223
	v_sub_f32_e32 v35, v41, v223
	v_sub_f32_e32 v36, v42, v223
	v_sub_f32_e32 v37, v43, v223
	v_sub_f32_e32 v39, v44, v223
	v_sub_f32_e32 v40, v45, v223
	v_sub_f32_e32 v41, v46, v223
	v_sub_f32_e32 v42, v47, v223
	v_sub_f32_e32 v43, v48, v223
	v_sub_f32_e32 v44, v49, v223
	v_sub_f32_e32 v45, v50, v223
	v_sub_f32_e32 v28, v28, v223
	v_exp_f32_e32 v29, v29
	v_exp_f32_e32 v179, v33
	v_exp_f32_e32 v181, v34
	v_exp_f32_e32 v153, v35
	v_exp_f32_e32 v180, v36
	v_exp_f32_e32 v151, v37
	v_exp_f32_e32 v178, v39
	v_exp_f32_e32 v150, v40
	v_exp_f32_e32 v152, v41
	v_exp_f32_e32 v147, v42
	v_exp_f32_e32 v149, v43
	v_exp_f32_e32 v145, v44
	v_exp_f32_e32 v148, v45
	v_exp_f32_e32 v143, v28
	v_and_b32_e32 v28, 0x3fffffc0, v81
	s_cmp_lg_u32 0, -1
	s_waitcnt vmcnt(3)
	v_lshl_add_u32 v28, v28, 2, 0
	s_cselect_b32 s0, 0, 0
	v_sub_f32_e32 v65, v15, v223
	v_mov_b32_e32 v15, 0
	v_add_u32_e32 v222, s0, v218
	v_cndmask_b32_e64 v213, v29, 1.0, vcc
	v_sub_f32_e32 v64, v14, v223
	v_sub_f32_e32 v67, v13, v223
	v_sub_f32_e32 v66, v12, v223
	v_sub_f32_e32 v69, v27, v223
	v_sub_f32_e32 v68, v26, v223
	v_sub_f32_e32 v71, v25, v223
	v_sub_f32_e32 v70, v24, v223
	v_sub_f32_e32 v73, v23, v223
	v_sub_f32_e32 v72, v22, v223
	v_sub_f32_e32 v75, v21, v223
	v_sub_f32_e32 v74, v20, v223
	v_sub_f32_e32 v77, v19, v223
	v_sub_f32_e32 v76, v18, v223
	v_sub_f32_e32 v79, v17, v223
	v_sub_f32_e32 v78, v16, v223
	s_waitcnt vmcnt(2)
	ds_write_b128 v219, v[0:3] offset:16384
	s_waitcnt vmcnt(1)
	ds_write_b128 v220, v[4:7] offset:16384
	s_waitcnt vmcnt(0)
	ds_write_b128 v221, v[8:11] offset:40960
	v_lshl_add_u32 v212, v204, 2, v28
	v_lshl_add_u32 v211, v38, 2, v28
	v_mov_b32_e32 v14, v15
	v_mov_b32_e32 v13, v15
	v_mov_b32_e32 v12, v15
	v_mov_b32_e32 v11, v15
	v_mov_b32_e32 v10, v15
	v_mov_b32_e32 v9, v15
	v_mov_b32_e32 v8, v15
	v_mov_b32_e32 v7, v15
	v_mov_b32_e32 v6, v15
	v_mov_b32_e32 v5, v15
	v_mov_b32_e32 v4, v15
	v_mov_b32_e32 v3, v15
	v_mov_b32_e32 v2, v15
	v_mov_b32_e32 v1, v15
	v_mov_b32_e32 v0, v15
	v_mov_b32_e32 v31, v15
	v_mov_b32_e32 v30, v15
	v_mov_b32_e32 v29, v15
	v_mov_b32_e32 v28, v15
	v_mov_b32_e32 v27, v15
	v_mov_b32_e32 v26, v15
	v_mov_b32_e32 v25, v15
	v_mov_b32_e32 v24, v15
	v_mov_b32_e32 v23, v15
	v_mov_b32_e32 v22, v15
	v_mov_b32_e32 v21, v15
	v_mov_b32_e32 v20, v15
	v_mov_b32_e32 v19, v15
	v_mov_b32_e32 v18, v15
	v_mov_b32_e32 v17, v15
	v_mov_b32_e32 v16, v15
	v_mov_b32_e32 v47, v15
	v_mov_b32_e32 v46, v15
	v_mov_b32_e32 v45, v15
	v_mov_b32_e32 v44, v15
	v_mov_b32_e32 v43, v15
	v_mov_b32_e32 v42, v15
	v_mov_b32_e32 v41, v15
	v_mov_b32_e32 v40, v15
	v_mov_b32_e32 v39, v15
	v_mov_b32_e32 v38, v15
	v_mov_b32_e32 v37, v15
	v_mov_b32_e32 v36, v15
	v_mov_b32_e32 v35, v15
	v_mov_b32_e32 v34, v15
	v_mov_b32_e32 v33, v15
	v_mov_b32_e32 v32, v15
	v_mov_b32_e32 v63, v15
	v_mov_b32_e32 v62, v15
	v_mov_b32_e32 v61, v15
	v_mov_b32_e32 v60, v15
	v_mov_b32_e32 v59, v15
	v_mov_b32_e32 v58, v15
	v_mov_b32_e32 v57, v15
	v_mov_b32_e32 v56, v15
	v_mov_b32_e32 v55, v15
	v_mov_b32_e32 v54, v15
	v_mov_b32_e32 v53, v15
	v_mov_b32_e32 v52, v15
	v_mov_b32_e32 v51, v15
	v_mov_b32_e32 v50, v15
	v_mov_b32_e32 v49, v15
	v_mov_b32_e32 v48, v15
	v_mov_b32_e32 v112, v15
	s_waitcnt lgkmcnt(0)
	s_barrier
	s_and_saveexec_b64 s[0:1], s[6:7]
	s_cbranch_execz .LBB0_168
	s_movk_i32 s6, 0xc00
	v_mad_i64_i32 v[0:1], s[2:3], v82, s6, 0
	v_mad_i64_i32 v[2:3], s[2:3], v83, s6, 0
	s_cmp_lg_u32 0, -1
	s_cselect_b32 s2, 0, 0
	s_addk_i32 s2, 0x4000
	v_add_u32_e32 v224, s2, v218
	s_mov_b32 s2, 0x30000
	v_mad_i64_i32 v[4:5], s[2:3], v80, s2, 0
	v_bfe_u32 v6, v203, 6, 1
	s_mov_b32 s2, 0x1800000
	v_mad_u64_u32 v[4:5], s[2:3], v6, s2, v[4:5]
	v_lshlrev_b32_e32 v6, 2, v203
	v_lshl_add_u64 v[2:3], v[4:5], 0, v[2:3]
	v_and_b32_e32 v112, 0x80, v6
	v_and_b32_e32 v6, 7, v81
	v_lshl_add_u64 v[2:3], v[2:3], 0, v[112:113]
	v_lshlrev_b32_e32 v112, 4, v6
	v_lshl_add_u64 v[2:3], v[2:3], 0, v[112:113]
	v_lshl_add_u64 v[174:175], s[90:91], 0, v[2:3]
	v_and_b32_e32 v2, 11, v81
	v_bfe_u32 v6, v81, 4, 1
	v_lshl_or_b32 v2, v6, 2, v2
	v_lshl_add_u64 v[0:1], v[4:5], 0, v[0:1]
	v_lshlrev_b32_e32 v112, 4, v2
	v_xor_b32_e32 v172, 0x80000000, v170
	v_lshl_add_u64 v[0:1], v[0:1], 0, v[112:113]
	v_mov_b32_e32 v112, 0
	v_mov_b32_e32 v173, v172
	v_cmp_gt_u32_e64 s[6:7], 32, v210
	v_mov_b32_e32 v167, v113
	s_movk_i32 s2, 0x80
	s_mov_b32 s3, 4
	v_lshl_add_u64 v[176:177], s[90:91], 0, v[0:1]
	s_mov_b64 s[20:21], 0
	v_mov_b32_e32 v48, 0
	v_mov_b32_e32 v49, v112
	v_mov_b32_e32 v50, v112
	v_mov_b32_e32 v51, v112
	v_mov_b32_e32 v52, v112
	v_mov_b32_e32 v53, v112
	v_mov_b32_e32 v54, v112
	v_mov_b32_e32 v55, v112
	v_mov_b32_e32 v56, v112
	v_mov_b32_e32 v57, v112
	v_mov_b32_e32 v58, v112
	v_mov_b32_e32 v59, v112
	v_mov_b32_e32 v60, v112
	v_mov_b32_e32 v61, v112
	v_mov_b32_e32 v62, v112
	v_mov_b32_e32 v63, v112
	v_mov_b32_e32 v32, 0
	v_mov_b32_e32 v33, v112
	v_mov_b32_e32 v34, v112
	v_mov_b32_e32 v35, v112
	v_mov_b32_e32 v36, v112
	v_mov_b32_e32 v37, v112
	v_mov_b32_e32 v38, v112
	v_mov_b32_e32 v39, v112
	v_mov_b32_e32 v40, v112
	v_mov_b32_e32 v41, v112
	v_mov_b32_e32 v42, v112
	v_mov_b32_e32 v43, v112
	v_mov_b32_e32 v44, v112
	v_mov_b32_e32 v45, v112
	v_mov_b32_e32 v46, v112
	v_mov_b32_e32 v47, v112
	v_mov_b32_e32 v16, 0
	v_mov_b32_e32 v17, v112
	v_mov_b32_e32 v18, v112
	v_mov_b32_e32 v19, v112
	v_mov_b32_e32 v20, v112
	v_mov_b32_e32 v21, v112
	v_mov_b32_e32 v22, v112
	v_mov_b32_e32 v23, v112
	v_mov_b32_e32 v24, v112
	v_mov_b32_e32 v25, v112
	v_mov_b32_e32 v26, v112
	v_mov_b32_e32 v27, v112
	v_mov_b32_e32 v28, v112
	v_mov_b32_e32 v29, v112
	v_mov_b32_e32 v30, v112
	v_mov_b32_e32 v31, v112
	v_mov_b32_e32 v0, 0
	v_mov_b32_e32 v1, v112
	v_mov_b32_e32 v2, v112
	v_mov_b32_e32 v3, v112
	v_mov_b32_e32 v4, v112
	v_mov_b32_e32 v5, v112
	v_mov_b32_e32 v6, v112
	v_mov_b32_e32 v7, v112
	v_mov_b32_e32 v8, v112
	v_mov_b32_e32 v9, v112
	v_mov_b32_e32 v10, v112
	v_mov_b32_e32 v11, v112
	v_mov_b32_e32 v12, v112
	v_mov_b32_e32 v13, v112
	v_mov_b32_e32 v14, v112
	v_mov_b32_e32 v15, v112
	s_branch .LBB0_158
